# static s_setprio 1 for waves 4-7 during the prep, compress and attention phases (non-GEMM MFMA+VALU phases)
# baseline (speedup 1.0000x reference)
.LBB0_409:
	v_readlane_b32 s2, v253, 59
	v_readlane_b32 s3, v253, 60
	s_andn2_b64 vcc, exec, s[4:5]
	s_nop 0
	v_cndmask_b32_e64 v0, 0, 1, s[2:3]
	v_cmp_ne_u32_e64 s[2:3], 1, v0
	s_nop 1
	v_writelane_b32 v255, s2, 26
	s_nop 1
	v_writelane_b32 v255, s3, 27
	s_cbranch_vccnz .LBB0_686
	s_cmp_ge_u32 s88, 4
	s_cbranch_scc0 .Lprio_0
	s_setprio 1
.Lprio_0:
	v_readlane_b32 s2, v255, 23
	v_readlane_b32 s18, v252, 2
	v_readlane_b32 s3, v255, 24
	v_mov_b32_e32 v0, v96
	v_readlane_b32 s19, v252, 3
	s_mov_b32 s3, s29
	s_load_dwordx4 s[20:23], s[18:19], 0x110
	v_writelane_b32 v255, s2, 23
	v_mbcnt_lo_u32_b32 v0, -1, v0
	v_mbcnt_hi_u32_b32 v102, -1, v0
	v_writelane_b32 v255, s3, 24
	s_movk_i32 s14, 0x7f
	v_readlane_b32 s2, v255, 26
	v_readlane_b32 s3, v255, 27
	v_add_u32_e32 v97, s90, v102
	s_and_b64 vcc, exec, s[2:3]
	v_cmp_gt_i32_e64 s[46:47], 8, v102
	v_cmp_gt_i32_e64 s[48:49], 16, v102
	s_cbranch_vccnz .LBB0_469
	v_readlane_b32 s4, v255, 23
	s_waitcnt lgkmcnt(0)
	s_load_dwordx4 s[8:11], s[18:19], 0x58
	v_readlane_b32 s5, v255, 24
	s_lshl_b64 s[2:3], s[4:5], 14
	s_lshl_b64 s[12:13], s[4:5], 12
	s_lshl_b32 s30, s4, 3
	s_waitcnt lgkmcnt(0)
	s_add_u32 s4, s22, 0xdea0200
	s_addc_u32 s5, s23, 0
	s_add_u32 s6, s8, s2
	s_addc_u32 s7, s9, s3
	s_movk_i32 s2, 0x280
	s_add_u32 s8, s10, s12
	v_add_u32_sdwa v103, v97, s2 dst_sel:DWORD dst_unused:UNUSED_PAD src0_sel:BYTE_0 src1_sel:DWORD
	v_lshlrev_b32_e32 v106, 1, v102
	v_readlane_b32 s2, v253, 20
	s_addc_u32 s9, s11, s13
	v_ashrrev_i32_e32 v0, 8, v97
	v_add_lshl_u32 v4, v106, s2, 2
	s_add_i32 s2, 0, 0x18000
	v_add_u32_e32 v154, s2, v4
	v_readlane_b32 s2, v254, 47
	v_lshlrev_b32_e32 v104, 6, v0
	v_cmp_lt_i32_e64 s[52:53], 0, v0
	v_add_u32_e32 v155, s2, v4
	v_readlane_b32 s2, v254, 48
	v_lshlrev_b32_e32 v2, 1, v97
	v_lshlrev_b32_e32 v0, 14, v0
	v_add_u32_e32 v156, s2, v4
	s_movk_i32 s2, 0x200
	v_or_b32_sdwa v157, v97, s2 dst_sel:DWORD dst_unused:UNUSED_PAD src0_sel:BYTE_0 src1_sel:DWORD
	s_movk_i32 s2, 0xf0
	v_and_b32_e32 v3, 0xf0, v2
	v_bitop3_b32 v2, v2, v0, s2 bitop3:0xce
	s_movk_i32 s2, 0xe0
	v_add_u32_e32 v160, 0, v2
	v_bitop3_b32 v2, v3, v0, s2 bitop3:0xde
	s_movk_i32 s2, 0xd0
	v_add_u32_e32 v161, 0, v2
	v_bitop3_b32 v2, v3, v0, s2 bitop3:0xde
	s_movk_i32 s2, 0xc0
	v_and_b32_e32 v1, 0x7f, v97
	v_add_u32_e32 v162, 0, v2
	v_bitop3_b32 v2, v3, v0, s2 bitop3:0xde
	s_movk_i32 s2, 0xb0
	v_lshl_add_u32 v152, v1, 8, 0
	v_lshlrev_b32_e32 v108, 1, v1
	v_bitop3_b32 v1, v3, v0, s2 bitop3:0xde
	s_movk_i32 s2, 0xa0
	v_add_u32_e32 v165, 0, v1
	v_bitop3_b32 v1, v3, v0, s2 bitop3:0xde
	s_movk_i32 s2, 0x90
	s_movk_i32 s3, 0x80
	v_add_u32_e32 v166, 0, v1
	v_bitop3_b32 v1, v3, v0, s2 bitop3:0xde
	v_add_u32_e32 v167, 0, v1
	v_bitop3_b32 v1, v3, v0, s3 bitop3:0xde
	s_movk_i32 s2, 0x70
	s_add_u32 s12, s22, 0x4ce0f200
	v_add_u32_e32 v168, 0, v1
	v_bitop3_b32 v1, v3, v0, s2 bitop3:0xde
	s_movk_i32 s2, 0x60
	s_addc_u32 s13, s23, 0
	v_add_u32_e32 v170, 0, v1
	v_bitop3_b32 v1, v3, v0, s2 bitop3:0xde
	s_movk_i32 s2, 0x50
	s_add_u32 s31, s22, 0x4ce8f200
	v_add_u32_e32 v171, 0, v1
	v_bitop3_b32 v1, v3, v0, s2 bitop3:0xde
	s_addc_u32 s74, s23, 0
	v_add_u32_e32 v172, 0, v1
	v_bitop3_b32 v1, v3, v0, 64 bitop3:0xde
	v_cmp_gt_u32_sdwa s[10:11], v97, s14 src0_sel:BYTE_0 src1_sel:DWORD
	s_add_u32 s14, s22, 0x18120200
	v_add_u32_e32 v173, 0, v1
	v_bitop3_b32 v1, v3, v0, 48 bitop3:0xde
	s_addc_u32 s15, s23, 0
	v_add_u32_e32 v185, 0, v1
	v_bitop3_b32 v1, v3, v0, 32 bitop3:0xde
	s_add_u32 s75, s22, 0x4d690200
	v_lshrrev_b32_e32 v158, 2, v104
	v_add_u32_e32 v186, 0, v1
	v_bitop3_b32 v1, v3, v0, 16 bitop3:0xde
	v_or_b32_e32 v0, v0, v3
	v_readlane_b32 s16, v254, 23
	v_cmp_lt_u32_sdwa s[50:51], v97, s3 src0_sel:BYTE_0 src1_sel:DWORD
	v_ashrrev_i32_e32 v105, 31, v104
	v_and_b32_e32 v109, 14, v106
	v_and_b32_e32 v153, 31, v102
	v_ashrrev_i32_e32 v107, 31, v106
	v_cmp_gt_i32_e64 s[54:55], 1, v102
	v_cmp_gt_i32_e64 s[56:57], 2, v102
	v_cmp_gt_i32_e64 s[58:59], 4, v102
	v_cmp_gt_i32_e64 s[60:61], 32, v102
	v_cmp_eq_u32_e64 s[62:63], 63, v102
	s_addc_u32 s76, s23, 0
	v_or_b32_e32 v159, 3, v158
	v_add_u32_e32 v163, 0, v2
	v_or_b32_e32 v164, 2, v158
	v_or_b32_e32 v169, 1, v158
	v_add_u32_e32 v187, 0, v1
	v_add_u32_e32 v188, 0, v0
	v_readlane_b32 s17, v254, 24
	s_mov_b32 s77, s86
	s_branch .LBB0_413

.LBB0_688:
	s_andn2_b64 vcc, exec, s[4:5]
	s_cbranch_vccnz .LBB0_1073
	s_cmp_ge_u32 s88, 4
	s_cbranch_scc0 .Lprio_1
	s_setprio 1
.Lprio_1:
	s_waitcnt lgkmcnt(0)
	v_readlane_b32 s10, v252, 2
	v_mov_b32_e32 v0, v96
	v_readlane_b32 s11, v252, 3
	s_load_dwordx4 s[12:15], s[10:11], 0x110
	v_mbcnt_lo_u32_b32 v0, -1, v0
	v_readlane_b32 s2, v253, 37
	v_mbcnt_hi_u32_b32 v134, -1, v0
	v_readlane_b32 s3, v253, 38
	s_mov_b32 s73, 0x1da6f000
	v_add_u32_e32 v16, s90, v134
	s_andn2_b64 vcc, exec, s[2:3]
	s_cbranch_vccnz .LBB0_703
	v_readlane_b32 s2, v255, 23
	v_readlane_b32 s3, v255, 24
	s_mov_b32 s3, s29
	s_lshl_b64 s[4:5], s[2:3], 14
	s_mov_b32 s6, s2
	s_lshl_b32 s22, s2, 1
	s_movk_i32 s2, 0x880
	v_cmp_gt_i32_e64 s[46:47], s2, v16
	v_and_b32_e32 v17, 15, v134
	v_readlane_b32 s2, v253, 39
	v_ashrrev_i32_e32 v0, 4, v134
	v_lshlrev_b32_e32 v4, 3, v0
	v_or_b32_e32 v18, s2, v17
	v_lshlrev_b32_e32 v0, 11, v0
	v_lshlrev_b32_e32 v1, 2, v18
	s_waitcnt lgkmcnt(0)
	s_add_u32 s23, s14, 0x50690200
	v_add3_u32 v19, 0, v0, v1
	v_and_b32_e32 v1, 7, v134
	v_writelane_b32 v255, s6, 23
	s_addc_u32 s24, s15, 0
	v_lshlrev_b32_e32 v2, 5, v1
	v_mov_b32_e32 v3, v96
	v_writelane_b32 v255, s7, 24
	s_add_u32 s6, s14, 0x50a90200
	v_lshl_add_u64 v[2:3], s[12:13], 0, v[2:3]
	s_mov_b64 s[2:3], 0x4100000
	s_addc_u32 s7, s15, 0
	v_ashrrev_i32_e32 v20, 5, v16
	v_lshl_add_u64 v[6:7], v[2:3], 0, s[2:3]
	s_add_i32 s2, 0, 0x9000
	v_lshlrev_b32_e32 v0, 1, v134
	v_lshlrev_b32_e32 v21, 4, v1
	v_lshl_add_u32 v22, v20, 9, s2
	v_and_b32_e32 v1, 31, v134
	v_readlane_b32 s2, v254, 59
	v_and_b32_e32 v0, 62, v0
	v_lshlrev_b32_e32 v2, 3, v1
	v_mov_b32_e32 v3, v96
	v_readlane_b32 s3, v254, 60
	v_ashrrev_i32_e32 v5, 31, v4
	s_waitcnt vmcnt(0)
	v_lshlrev_b32_e32 v10, 2, v0
	v_lshl_add_u64 v[8:9], s[2:3], 0, v[2:3]
	s_mov_b32 s25, s86
	s_branch .LBB0_692

.Lprio_2:
	v_readlane_b32 s2, v252, 2
	v_mov_b32_e32 v0, v96
	v_readlane_b32 s3, v252, 3
	s_nop 0
	v_writelane_b32 v255, s2, 36
	s_load_dwordx4 s[60:63], s[2:3], 0x110
	v_mbcnt_lo_u32_b32 v0, -1, v0
	v_writelane_b32 v255, s3, 37
	v_mbcnt_hi_u32_b32 v116, -1, v0
	v_readlane_b32 s2, v255, 26
	v_readlane_b32 s3, v255, 27
	s_and_b64 vcc, exec, s[2:3]
	s_cbranch_vccnz .LBB0_1267
	v_readlane_b32 s2, v255, 23
	s_lshl_b32 s27, s2, 14
	s_waitcnt lgkmcnt(0)
	s_add_u32 s38, s62, 0x4c5ef200
	s_addc_u32 s39, s63, 0
	s_add_u32 s31, s62, 0x1ba00200
	s_addc_u32 s33, s63, 0
	s_add_u32 s2, s62, 0x1ba3fa00
	v_readlane_b32 s3, v255, 24
	v_writelane_b32 v255, s2, 38
	s_addc_u32 s2, s63, 0
	v_writelane_b32 v255, s2, 39
	s_add_u32 s2, s62, 0x1b1e0200
	s_addc_u32 s3, s63, 0
	v_writelane_b32 v255, s2, 33
	v_add_u32_e32 v117, s90, v116
	s_mov_b32 s11, s86
	v_writelane_b32 v255, s3, 34
	v_writelane_b32 v255, s60, 40
	s_nop 1
	v_writelane_b32 v255, s61, 41
	v_writelane_b32 v255, s62, 42
	v_writelane_b32 v255, s63, 43
	v_writelane_b32 v255, s27, 44
	v_writelane_b32 v255, s38, 45
	s_nop 1
	v_writelane_b32 v255, s39, 46
	v_writelane_b32 v255, s31, 47
	v_writelane_b32 v255, s33, 48
	s_branch .LBB0_1079
